# speedup vs baseline: 1.0265x; 1.0043x over previous
; DI unsigned cvtpk(float lo, float hi) { f32x2_t v = {lo, hi}; bf16x2_t b = __builtin_convertvector(v, bf16x2_t); return __builtin_bit_cast(unsigned, b); }
; DI int crow(int g, int h) { return (g & 3) + 8 * (g >> 2) + 4 * h; }
; template <bool GLA, int MODE> ...
;     ...
;             for (int kt = 0; kt < KT; ++kt)
; #pragma unroll
;                 for (int s = 0; s < 2; ++s) {
;                     u32x4 pw; pw.x = cvtpk(S[kt][8 * s + 0], S[kt][8 * s + 1]); pw.y = cvtpk(S[kt][8 * s + 2], S[kt][8 * s + 3]); pw.z = cvtpk(S[kt][8 * s + 4], S[kt][8 * s + 5]); pw.w = cvtpk(S[kt][8 * s + 6], S[kt][8 * s + 7]);
;                     const bf16x8 sb = __builtin_bit_cast(bf16x8, pw);
; #pragma unroll
;                     for (int it = 0; it < 2; ++it) {
;                         const unsigned char* qp = lds + S_QE + (32 * it + r) * S_QES + (hu * DK + 32 * kt + 16 * s + 4 * hh) * 2;
;                         const u32x2 lo = *(const u32x2*)qp, hi = *(const u32x2*)(qp + 16);
;                         u32x4 av; av.x = lo.x; av.y = lo.y; av.z = hi.x; av.w = hi.y;
;                         oa[it] = MFMA32(__builtin_bit_cast(bf16x8, av), sb, oa[it]);
;                     }
;                 }
; #pragma unroll
;         for (int i = 0; i < 4; ++i) *(u32x4*)(lds + S_VT + (tid >> 1) * S_TS + (16 * i + 8 * (tid & 1)) * 2) = vv[i];
;             __syncthreads();
;         }
; #pragma unroll
;         for (int js = 0; js < 4; ++js) {
;             const bf16x8 vb = *(const bf16x8*)(lds + S_VT + (hu * DVH + dv0 + r) * S_TS + (16 * js + 8 * hh) * 2);
;             if (MODE == 0) {
;                 if (js < 2) { const bf16x8 a0 = *(const bf16x8*)(lds + S_ATT + hu * 64 * S_TS + r * S_TS + (16 * js + 8 * hh) * 2); oa[0] = MFMA32(a0, vb, oa[0]); }
;                 { const bf16x8 a1 = *(const bf16x8*)(lds + S_ATT + hu * 64 * S_TS + (32 + r) * S_TS + (16 * js + 8 * hh) * 2); oa[1] = MFMA32(a1, vb, oa[1]); }
;             }
; #pragma unroll
;             for (int kt = 0; kt < KT; ++kt) {
;                 const bf16x8 ka = *(const bf16x8*)(lds + S_KST + (hu * DK + 32 * kt + r) * S_TS + (16 * js + 8 * hh) * 2);
;                 S[kt] = MFMA32(ka, vb, S[kt]);
;             }
;         }
; #pragma unroll
;         for (int kt = 0; kt < KT; ++kt)
; #pragma unroll
;             for (int g = 0; g < 16; ++g) S[kt][g] *= DEC[hu * DK + 32 * kt + crow(g, hh)];
.LBB0_1379:
	s_or_b64 exec, exec, s[86:87]
	ds_read2_b64 v[34:37], v134 offset1:2
	ds_read2_b64 v[142:145], v134 offset0:4 offset1:6
	v_cvt_pk_bf16_f32 v50, v18, v19
	v_cvt_pk_bf16_f32 v51, v20, v21
	v_cvt_pk_bf16_f32 v52, v22, v23
	v_cvt_pk_bf16_f32 v53, v24, v25
	v_add_u32_e32 v150, 0x2000, v134
	ds_read2_b64 v[54:57], v150 offset0:64 offset1:66
	s_waitcnt lgkmcnt(2)
	v_mfma_f32_32x32x16_bf16 v[34:49], v[34:37], v[50:53], 0
	v_cvt_pk_bf16_f32 v146, v26, v27
	v_cvt_pk_bf16_f32 v147, v28, v29
	v_cvt_pk_bf16_f32 v148, v30, v31
	v_cvt_pk_bf16_f32 v149, v32, v33
	s_add_i32 s5, s5, 64
	s_cmp_eq_u32 s38, s9
	s_waitcnt lgkmcnt(1)
	v_mfma_f32_32x32x16_bf16 v[34:49], v[142:145], v[146:149], v[34:49]
	ds_read2_b64 v[142:145], v150 offset0:68 offset1:70
	s_waitcnt lgkmcnt(1)
	v_mfma_f32_32x32x16_bf16 v[50:65], v[54:57], v[50:53], 0
	s_waitcnt lgkmcnt(0)
	v_mfma_f32_32x32x16_bf16 v[50:65], v[142:145], v[146:149], v[50:65]
	ds_read2_b64 v[146:149], v134 offset0:8 offset1:10
	v_cvt_pk_bf16_f32 v142, v2, v3
	v_cvt_pk_bf16_f32 v143, v4, v5
	v_cvt_pk_bf16_f32 v144, v6, v7
	v_cvt_pk_bf16_f32 v145, v8, v9
	s_waitcnt lgkmcnt(0)
	s_nop 0
	v_mfma_f32_32x32x16_bf16 v[34:49], v[146:149], v[142:145], v[34:49]
	ds_read2_b64 v[146:149], v150 offset0:72 offset1:74
	s_waitcnt lgkmcnt(0)
	v_mfma_f32_32x32x16_bf16 v[50:65], v[146:149], v[142:145], v[50:65]
	ds_read2_b64 v[146:149], v134 offset0:12 offset1:14
	v_cvt_pk_bf16_f32 v142, v10, v11
	v_cvt_pk_bf16_f32 v143, v12, v13
	v_cvt_pk_bf16_f32 v144, v14, v15
	v_cvt_pk_bf16_f32 v145, v16, v17
	s_waitcnt lgkmcnt(0)
	s_nop 0
	v_mfma_f32_32x32x16_bf16 v[34:49], v[146:149], v[142:145], v[34:49]
	ds_read2_b64 v[146:149], v150 offset0:76 offset1:78
	s_waitcnt vmcnt(3)
	ds_write_b128 v135, v[82:85] offset:53248
	s_waitcnt vmcnt(2)
	ds_write_b128 v135, v[86:89] offset:53280
	s_waitcnt vmcnt(1)
	ds_write_b128 v135, v[90:93] offset:53312
	s_waitcnt vmcnt(0)
	ds_write_b128 v135, v[94:97] offset:53344
	s_waitcnt lgkmcnt(0)
	s_barrier
	ds_read_b128 v[82:85], v136 offset:53248
	ds_read_b128 v[86:89], v136 offset:53280
	ds_read_b128 v[90:93], v137
	ds_read_b128 v[94:97], v137 offset:32
	v_mfma_f32_32x32x16_bf16 v[50:65], v[146:149], v[142:145], v[50:65]
	s_waitcnt lgkmcnt(1)
	v_mfma_f32_32x32x16_bf16 v[34:49], v[90:93], v[82:85], v[34:49]
	ds_read_b128 v[90:93], v137 offset:4608
	ds_read_b128 v[142:145], v138 offset:34816
	ds_read_b128 v[146:149], v138 offset:34848
	s_waitcnt lgkmcnt(1)
	v_mfma_f32_32x32x16_bf16 v[18:33], v[142:145], v[82:85], v[18:33]
	ds_read_b128 v[142:145], v138 offset:39424
	s_waitcnt lgkmcnt(0)
	v_mfma_f32_32x32x16_bf16 v[2:17], v[142:145], v[82:85], v[2:17]
	v_mfma_f32_32x32x16_bf16 v[50:65], v[90:93], v[82:85], v[50:65]
	ds_read_b128 v[82:85], v137 offset:4640
	ds_read_b128 v[90:93], v138 offset:39456
	v_mfma_f32_32x32x16_bf16 v[18:33], v[146:149], v[86:89], v[18:33]
	v_mfma_f32_32x32x16_bf16 v[34:49], v[94:97], v[86:89], v[34:49]
	s_waitcnt lgkmcnt(0)
	v_mfma_f32_32x32x16_bf16 v[2:17], v[90:93], v[86:89], v[2:17]
	s_nop 9
	v_cvt_pk_bf16_f32 v34, v34, s0
	v_mfma_f32_32x32x16_bf16 v[50:65], v[82:85], v[86:89], v[50:65]
	ds_read_b128 v[82:85], v136 offset:53312
	ds_read_b128 v[86:89], v137 offset:4672
	ds_read_b128 v[90:93], v138 offset:34880
	s_waitcnt lgkmcnt(0)
	v_mfma_f32_32x32x16_bf16 v[18:33], v[90:93], v[82:85], v[18:33]
	ds_read_b128 v[90:93], v138 offset:39488
	s_waitcnt lgkmcnt(0)
	v_mfma_f32_32x32x16_bf16 v[2:17], v[90:93], v[82:85], v[2:17]
	v_mfma_f32_32x32x16_bf16 v[50:65], v[86:89], v[82:85], v[50:65]
	ds_read_b128 v[82:85], v136 offset:53344
	ds_read_b128 v[86:89], v137 offset:4704
	ds_read_b128 v[90:93], v138 offset:34912
	s_waitcnt lgkmcnt(0)
	v_mfma_f32_32x32x16_bf16 v[18:33], v[90:93], v[82:85], v[18:33]
	ds_read_b128 v[90:93], v138 offset:39520
	s_waitcnt lgkmcnt(0)
	v_mfma_f32_32x32x16_bf16 v[2:17], v[90:93], v[82:85], v[2:17]
	v_mfma_f32_32x32x16_bf16 v[50:65], v[86:89], v[82:85], v[50:65]
	ds_read_b128 v[82:85], v139
	ds_read_b128 v[86:89], v139 offset:32
	s_waitcnt lgkmcnt(1)
	s_nop 4
	v_mul_f32_e64 v18, v18, v82
	v_mul_f32_e64 v19, v19, v83
	v_pk_mul_f32 v[20:21], v[20:21], v[84:85]
	ds_read_b128 v[82:85], v139 offset:64
	s_waitcnt lgkmcnt(1)
	v_pk_mul_f32 v[24:25], v[24:25], v[88:89]
	v_pk_mul_f32 v[22:23], v[22:23], v[86:87]
	s_waitcnt lgkmcnt(0)
	v_pk_mul_f32 v[26:27], v[26:27], v[82:83]
	v_pk_mul_f32 v[28:29], v[28:29], v[84:85]
	ds_read_b128 v[82:85], v139 offset:96
	s_waitcnt lgkmcnt(0)
	v_pk_mul_f32 v[30:31], v[30:31], v[82:83]
	v_pk_mul_f32 v[32:33], v[32:33], v[84:85]
	ds_read_b128 v[82:85], v139 offset:128
	s_waitcnt lgkmcnt(0)
	v_pk_mul_f32 v[2:3], v[2:3], v[82:83]
	v_pk_mul_f32 v[4:5], v[4:5], v[84:85]
	ds_read_b128 v[82:85], v139 offset:160
	s_waitcnt lgkmcnt(0)
	v_pk_mul_f32 v[6:7], v[6:7], v[82:83]
	v_pk_mul_f32 v[8:9], v[8:9], v[84:85]
	ds_read_b128 v[82:85], v139 offset:192
	s_waitcnt lgkmcnt(0)
	v_pk_mul_f32 v[10:11], v[10:11], v[82:83]
	v_pk_mul_f32 v[12:13], v[12:13], v[84:85]
	ds_read_b128 v[82:85], v139 offset:224
	s_waitcnt lgkmcnt(0)
	s_barrier
; DI unsigned short f2bf(float f) { return (unsigned short)(cvtpk(f, 0.f) & 0xffffu); }
; DI float bflo(unsigned w) { return __uint_as_float(w << 16); }
; DI float bfhi(unsigned w) { return __uint_as_float(w & 0xffff0000u); }
; DI int crow(int g, int h) { return (g & 3) + 8 * (g >> 2) + 4 * h; }
; template <bool GLA, int MODE> ...
;     ...
;                 unsigned short* OB = (unsigned short*)(lds + S_OB);
; #pragma unroll
;                 for (int it = 0; it < 2; ++it)
; #pragma unroll
;                     for (int g = 0; g < 16; ++g) OB[(32 * it + crow(g, hh)) * (S_OBS / 2) + hu * DVH + dv0 + r] = f2bf(oa[it][g]);
;             }
;             __syncthreads();
;             {
;                 const int i = tid >> 3, p = tid & 7;
;                 const u32x4* src = (const u32x4*)(lds + S_OB + i * S_OBS + p * 64);
;                 float x[32];
; #pragma unroll
;                 for (int q = 0; q < 4; ++q) { const u32x4 w = src[q];
;                     x[8 * q + 0] = bflo(w.x); x[8 * q + 1] = bfhi(w.x); x[8 * q + 2] = bflo(w.y); x[8 * q + 3] = bfhi(w.y);
;                     x[8 * q + 4] = bflo(w.z); x[8 * q + 5] = bfhi(w.z); x[8 * q + 6] = bflo(w.w); x[8 * q + 7] = bfhi(w.w); }
;                 float s = 0.f;
;                 if (!GLA) {
; #pragma unroll
;                     for (int q = 0; q < 32; ++q) s += x[q];
;                     s += __shfl_xor(s, 1); s += __shfl_xor(s, 2);
;                     const float mean = s * (1.f / 128.f);
; #pragma unroll
;                     for (int q = 0; q < 32; ++q) x[q] -= mean;
;                 }
;                 float s2 = 0.f;
; #pragma unroll
;                 for (int q = 0; q < 32; ++q) s2 += x[q] * x[q];
;                 s2 += __shfl_xor(s2, 1); s2 += __shfl_xor(s2, 2); if (GLA) s2 += __shfl_xor(s2, 4);
;                 const float rstd = 1.f / sqrtf(s2 * (1.f / DVH) + EPS);
;                 const float* gp = gain + 32 * p;
	ds_write_b16 v140, v34
	v_cvt_pk_bf16_f32 v34, v35, s0
	ds_write_b16 v140, v34 offset:528
	v_cvt_pk_bf16_f32 v34, v36, s0
	ds_write_b16 v140, v34 offset:1056
	v_cvt_pk_bf16_f32 v34, v37, s0
	ds_write_b16 v140, v34 offset:1584
	v_cvt_pk_bf16_f32 v34, v38, s0
	ds_write_b16 v140, v34 offset:4224
	v_cvt_pk_bf16_f32 v34, v39, s0
	ds_write_b16 v140, v34 offset:4752
	v_cvt_pk_bf16_f32 v34, v40, s0
	ds_write_b16 v140, v34 offset:5280
	v_cvt_pk_bf16_f32 v34, v41, s0
	ds_write_b16 v140, v34 offset:5808
	v_cvt_pk_bf16_f32 v34, v42, s0
	ds_write_b16 v140, v34 offset:8448
	v_cvt_pk_bf16_f32 v34, v43, s0
	ds_write_b16 v140, v34 offset:8976
	v_cvt_pk_bf16_f32 v34, v44, s0
	ds_write_b16 v140, v34 offset:9504
	v_cvt_pk_bf16_f32 v34, v45, s0
	ds_write_b16 v140, v34 offset:10032
	v_cvt_pk_bf16_f32 v34, v46, s0
	ds_write_b16 v140, v34 offset:12672
	v_cvt_pk_bf16_f32 v34, v47, s0
	ds_write_b16 v140, v34 offset:13200
	v_cvt_pk_bf16_f32 v34, v48, s0
	ds_write_b16 v140, v34 offset:13728
	v_cvt_pk_bf16_f32 v34, v49, s0
	ds_write_b16 v140, v34 offset:14256
	v_cvt_pk_bf16_f32 v34, v50, s0
	ds_write_b16 v140, v34 offset:16896
	v_cvt_pk_bf16_f32 v34, v51, s0
	ds_write_b16 v140, v34 offset:17424
	v_cvt_pk_bf16_f32 v34, v52, s0
	ds_write_b16 v140, v34 offset:17952
	v_cvt_pk_bf16_f32 v34, v53, s0
	ds_write_b16 v140, v34 offset:18480
	v_cvt_pk_bf16_f32 v34, v54, s0
	ds_write_b16 v140, v34 offset:21120
	v_cvt_pk_bf16_f32 v34, v55, s0
	ds_write_b16 v140, v34 offset:21648
	v_cvt_pk_bf16_f32 v34, v56, s0
	ds_write_b16 v140, v34 offset:22176
	v_cvt_pk_bf16_f32 v34, v57, s0
	ds_write_b16 v140, v34 offset:22704
	v_cvt_pk_bf16_f32 v34, v58, s0
	ds_write_b16 v140, v34 offset:25344
	v_cvt_pk_bf16_f32 v34, v59, s0
	ds_write_b16 v140, v34 offset:25872
	v_cvt_pk_bf16_f32 v34, v60, s0
	ds_write_b16 v140, v34 offset:26400
	v_cvt_pk_bf16_f32 v34, v61, s0
	ds_write_b16 v140, v34 offset:26928
	v_cvt_pk_bf16_f32 v34, v62, s0
	ds_write_b16 v140, v34 offset:29568
	v_cvt_pk_bf16_f32 v34, v63, s0
	ds_write_b16 v140, v34 offset:30096
	v_cvt_pk_bf16_f32 v34, v64, s0
	ds_write_b16 v140, v34 offset:30624
	v_cvt_pk_bf16_f32 v34, v65, s0
	ds_write_b16 v140, v34 offset:31152
	s_waitcnt lgkmcnt(0)
	s_barrier
	ds_read_b128 v[44:47], v141
	ds_read_b128 v[48:51], v141 offset:16
	ds_read_b128 v[52:55], v141 offset:32
	ds_read_b128 v[56:59], v141 offset:48
	v_pk_mul_f32 v[16:17], v[16:17], v[84:85]
	s_waitcnt lgkmcnt(3)
	v_lshlrev_b32_e32 v64, 16, v44
	v_and_b32_e32 v65, 0xffff0000, v44
	v_add_f32_e32 v44, 0, v64
	v_lshlrev_b32_e32 v62, 16, v46
	v_and_b32_e32 v63, 0xffff0000, v46
	v_lshlrev_b32_e32 v46, 16, v45
	v_add_f32_e32 v44, v44, v65
	v_lshlrev_b32_e32 v60, 16, v47
	v_and_b32_e32 v61, 0xffff0000, v47
	v_and_b32_e32 v47, 0xffff0000, v45
	v_add_f32_e32 v44, v44, v46
	v_add_f32_e32 v44, v44, v47
	v_add_f32_e32 v44, v44, v62
	v_add_f32_e32 v44, v44, v63
	v_add_f32_e32 v44, v44, v60
	v_add_f32_e32 v90, v44, v61
	s_waitcnt lgkmcnt(2)
	v_lshlrev_b32_e32 v88, 16, v48
	v_and_b32_e32 v89, 0xffff0000, v48
	v_add_f32_e32 v48, v90, v88
	v_lshlrev_b32_e32 v86, 16, v50
	v_and_b32_e32 v87, 0xffff0000, v50
	v_lshlrev_b32_e32 v50, 16, v49
	v_add_f32_e32 v48, v48, v89
	v_lshlrev_b32_e32 v84, 16, v51
	v_and_b32_e32 v85, 0xffff0000, v51
	v_and_b32_e32 v51, 0xffff0000, v49
	v_add_f32_e32 v48, v48, v50
	v_add_f32_e32 v48, v48, v51
	v_add_f32_e32 v48, v48, v86
	v_add_f32_e32 v48, v48, v87
	v_add_f32_e32 v48, v48, v84
	v_pk_mul_f32 v[14:15], v[14:15], v[82:83]
	s_waitcnt lgkmcnt(0)
	v_and_b32_e32 v44, 0xffff0000, v59
	v_lshlrev_b32_e32 v45, 16, v59
	v_and_b32_e32 v82, 0xffff0000, v58
	v_lshlrev_b32_e32 v83, 16, v58
	v_and_b32_e32 v58, 0xffff0000, v57
	v_lshlrev_b32_e32 v59, 16, v57
	v_add_f32_e32 v57, v48, v85
	v_lshlrev_b32_e32 v92, 16, v52
	v_and_b32_e32 v93, 0xffff0000, v52
	v_add_f32_e32 v52, v57, v92
	v_lshlrev_b32_e32 v90, 16, v54
	v_and_b32_e32 v91, 0xffff0000, v54
	v_lshlrev_b32_e32 v54, 16, v53
	v_add_f32_e32 v52, v52, v93
	v_lshlrev_b32_e32 v48, 16, v55
	v_and_b32_e32 v49, 0xffff0000, v55
	v_and_b32_e32 v55, 0xffff0000, v53
	v_add_f32_e32 v52, v52, v54
	v_add_f32_e32 v52, v52, v55
	v_add_f32_e32 v52, v52, v90
	v_add_f32_e32 v52, v52, v91
	v_add_f32_e32 v52, v52, v48
	v_add_f32_e32 v57, v52, v49
	v_lshlrev_b32_e32 v52, 16, v56
	v_and_b32_e32 v53, 0xffff0000, v56
	v_add_f32_e32 v56, v57, v52
	v_add_f32_e32 v56, v56, v53
	v_add_f32_e32 v56, v56, v59
	v_and_b32_e32 v35, 64, v220
	v_add_f32_e32 v56, v56, v58
	v_xor_b32_e32 v34, 1, v220
	v_add_u32_e32 v35, 64, v35
	v_add_f32_e32 v56, v56, v83
	v_cmp_lt_i32_e32 vcc, v34, v35
	v_add_f32_e32 v56, v56, v82
	v_add_f32_e32 v56, v56, v45
	v_cndmask_b32_e32 v34, v220, v34, vcc
	v_lshlrev_b32_e32 v168, 2, v34
	v_add_f32_e32 v56, v56, v44
	ds_bpermute_b32 v57, v168, v56
	v_xor_b32_e32 v34, 2, v220
	v_cmp_lt_i32_e32 vcc, v34, v35
	s_waitcnt lgkmcnt(0)
	v_add_f32_e32 v56, v56, v57
	v_cndmask_b32_e32 v34, v220, v34, vcc
	v_lshlrev_b32_e32 v169, 2, v34
	v_add_u32_e32 v34, s6, v112
	v_ashrrev_i32_e32 v35, 31, v34
	ds_bpermute_b32 v57, v169, v56
	v_lshlrev_b64 v[34:35], 10, v[34:35]
	v_lshl_add_u64 v[42:43], v[106:107], 0, v[34:35]
	global_load_dwordx4 v[34:37], v[104:105], off offset:16
	global_load_dwordx4 v[38:41], v[104:105], off
	global_load_dwordx4 v[198:201], v[104:105], off offset:48
	global_load_dwordx4 v[202:205], v[104:105], off offset:32
	global_load_dwordx4 v[206:209], v[104:105], off offset:80
	global_load_dwordx4 v[226:229], v[104:105], off offset:64
	global_load_dwordx4 v[230:233], v[104:105], off offset:112
	global_load_dwordx4 v[234:237], v[104:105], off offset:96
	s_mov_b32 s6, 0xf800000
	s_waitcnt lgkmcnt(0)
; DI unsigned cvtpk(float lo, float hi) { f32x2_t v = {lo, hi}; bf16x2_t b = __builtin_convertvector(v, bf16x2_t); return __builtin_bit_cast(unsigned, b); }
; template <bool GLA, int MODE> ...
;     ...
;                     const float mean = s * (1.f / 128.f);
; #pragma unroll
;                     for (int q = 0; q < 32; ++q) x[q] -= mean;
;                 }
;                 float s2 = 0.f;
; #pragma unroll
;                 for (int q = 0; q < 32; ++q) s2 += x[q] * x[q];
;                 s2 += __shfl_xor(s2, 1); s2 += __shfl_xor(s2, 2); if (GLA) s2 += __shfl_xor(s2, 4);
;                 const float rstd = 1.f / sqrtf(s2 * (1.f / DVH) + EPS);
;                 const float* gp = gain + 32 * p;
;                 u32x4* dst = (u32x4*)(OUT + (size_t)(row0 + i) * out_ld + ocol0 + 32 * p);
; #pragma unroll
;                 for (int q = 0; q < 4; ++q) {
;                     u32x4 w;
;                     w.x = cvtpk(x[8 * q + 0] * rstd * gp[8 * q + 0], x[8 * q + 1] * rstd * gp[8 * q + 1]);
;                     w.y = cvtpk(x[8 * q + 2] * rstd * gp[8 * q + 2], x[8 * q + 3] * rstd * gp[8 * q + 3]);
;                     w.z = cvtpk(x[8 * q + 4] * rstd * gp[8 * q + 4], x[8 * q + 5] * rstd * gp[8 * q + 5]);
;                     w.w = cvtpk(x[8 * q + 6] * rstd * gp[8 * q + 6], x[8 * q + 7] * rstd * gp[8 * q + 7]);
;                     dst[q] = w;
;                 }
	v_add_f32_e32 v56, v56, v57
	v_mul_f32_e32 v56, 0x3c000000, v56
	v_pk_add_f32 v[64:65], v[64:65], v[56:57] op_sel_hi:[1,0] neg_lo:[0,1] neg_hi:[0,1]
	v_pk_add_f32 v[46:47], v[46:47], v[56:57] op_sel_hi:[1,0] neg_lo:[0,1] neg_hi:[0,1]
	v_pk_add_f32 v[62:63], v[62:63], v[56:57] op_sel_hi:[1,0] neg_lo:[0,1] neg_hi:[0,1]
	v_pk_add_f32 v[60:61], v[60:61], v[56:57] op_sel_hi:[1,0] neg_lo:[0,1] neg_hi:[0,1]
	v_pk_add_f32 v[88:89], v[88:89], v[56:57] op_sel_hi:[1,0] neg_lo:[0,1] neg_hi:[0,1]
	v_pk_add_f32 v[50:51], v[50:51], v[56:57] op_sel_hi:[1,0] neg_lo:[0,1] neg_hi:[0,1]
	v_pk_add_f32 v[86:87], v[86:87], v[56:57] op_sel_hi:[1,0] neg_lo:[0,1] neg_hi:[0,1]
	v_pk_add_f32 v[84:85], v[84:85], v[56:57] op_sel_hi:[1,0] neg_lo:[0,1] neg_hi:[0,1]
	v_pk_add_f32 v[92:93], v[92:93], v[56:57] op_sel_hi:[1,0] neg_lo:[0,1] neg_hi:[0,1]
	v_pk_add_f32 v[54:55], v[54:55], v[56:57] op_sel_hi:[1,0] neg_lo:[0,1] neg_hi:[0,1]
	v_pk_add_f32 v[90:91], v[90:91], v[56:57] op_sel_hi:[1,0] neg_lo:[0,1] neg_hi:[0,1]
	v_pk_add_f32 v[48:49], v[48:49], v[56:57] op_sel_hi:[1,0] neg_lo:[0,1] neg_hi:[0,1]
	v_pk_add_f32 v[52:53], v[52:53], v[56:57] op_sel_hi:[1,0] neg_lo:[0,1] neg_hi:[0,1]
	v_pk_add_f32 v[58:59], v[58:59], v[56:57] op_sel_hi:[1,0] neg_lo:[0,1] neg_hi:[0,1]
	v_pk_add_f32 v[82:83], v[82:83], v[56:57] op_sel_hi:[1,0] neg_lo:[0,1] neg_hi:[0,1]
	v_pk_add_f32 v[44:45], v[44:45], v[56:57] op_sel_hi:[1,0] neg_lo:[0,1] neg_hi:[0,1]
	v_pk_mul_f32 v[56:57], v[64:65], v[64:65]
	v_pk_mul_f32 v[94:95], v[46:47], v[46:47]
	v_add_f32_e32 v56, v56, v57
	v_add_f32_e32 v56, v94, v56
	v_pk_mul_f32 v[96:97], v[62:63], v[62:63]
	v_add_f32_e32 v56, v95, v56
	v_add_f32_e32 v56, v96, v56
	v_pk_mul_f32 v[142:143], v[60:61], v[60:61]
	v_add_f32_e32 v56, v97, v56
	v_add_f32_e32 v56, v142, v56
	v_pk_mul_f32 v[144:145], v[88:89], v[88:89]
	v_add_f32_e32 v56, v143, v56
	v_add_f32_e32 v56, v144, v56
	v_pk_mul_f32 v[146:147], v[50:51], v[50:51]
	v_add_f32_e32 v56, v145, v56
	v_add_f32_e32 v56, v146, v56
	v_pk_mul_f32 v[148:149], v[86:87], v[86:87]
	v_add_f32_e32 v56, v147, v56
	v_add_f32_e32 v56, v148, v56
	v_pk_mul_f32 v[150:151], v[84:85], v[84:85]
	v_add_f32_e32 v56, v149, v56
	v_add_f32_e32 v56, v150, v56
	v_pk_mul_f32 v[152:153], v[92:93], v[92:93]
	v_add_f32_e32 v56, v151, v56
	v_add_f32_e32 v56, v152, v56
	v_pk_mul_f32 v[154:155], v[54:55], v[54:55]
	v_add_f32_e32 v56, v153, v56
	v_add_f32_e32 v56, v154, v56
	v_pk_mul_f32 v[156:157], v[90:91], v[90:91]
	v_add_f32_e32 v56, v155, v56
	v_add_f32_e32 v56, v156, v56
	v_pk_mul_f32 v[158:159], v[48:49], v[48:49]
	v_add_f32_e32 v56, v157, v56
	v_add_f32_e32 v56, v158, v56
	v_pk_mul_f32 v[160:161], v[52:53], v[52:53]
	v_add_f32_e32 v56, v159, v56
	v_add_f32_e32 v56, v160, v56
	v_pk_mul_f32 v[162:163], v[58:59], v[58:59]
	v_add_f32_e32 v56, v161, v56
	v_add_f32_e32 v56, v163, v56
	v_pk_mul_f32 v[164:165], v[82:83], v[82:83]
	v_add_f32_e32 v56, v162, v56
	v_add_f32_e32 v56, v165, v56
	v_pk_mul_f32 v[166:167], v[44:45], v[44:45]
	v_add_f32_e32 v56, v164, v56
	v_add_f32_e32 v56, v167, v56
	v_add_f32_e32 v56, v166, v56
	ds_bpermute_b32 v57, v168, v56
	s_waitcnt lgkmcnt(0)
	v_add_f32_e32 v56, v56, v57
	ds_bpermute_b32 v57, v169, v56
	s_waitcnt lgkmcnt(0)
	v_add_f32_e32 v56, v56, v57
	v_fmamk_f32 v56, v56, 0x3c000000, v214
	v_cmp_gt_f32_e32 vcc, s6, v56
	v_mul_f32_e32 v57, 0x4f800000, v56
	s_nop 0
	v_cndmask_b32_e32 v56, v56, v57, vcc
	v_sqrt_f32_e32 v57, v56
	s_nop 0
	v_add_u32_e32 v94, -1, v57
	v_fma_f32 v95, -v94, v57, v56
	v_cmp_ge_f32_e64 s[86:87], 0, v95
	v_add_u32_e32 v95, 1, v57
	s_nop 0
	v_cndmask_b32_e64 v94, v57, v94, s[86:87]
	v_fma_f32 v57, -v95, v57, v56
	v_cmp_lt_f32_e64 s[86:87], 0, v57
	s_nop 1
	v_cndmask_b32_e64 v57, v94, v95, s[86:87]
	v_mul_f32_e32 v94, 0x37800000, v57
	v_cndmask_b32_e32 v57, v57, v94, vcc
	v_cmp_class_f32_e32 vcc, v56, v215
	s_nop 1
	v_cndmask_b32_e32 v56, v57, v56, vcc
	v_div_scale_f32 v57, s[6:7], v56, v56, 1.0
	v_rcp_f32_e32 v94, v57
	s_nop 0
	v_fma_f32 v95, -v57, v94, 1.0
	v_fmac_f32_e32 v94, v95, v94
	v_div_scale_f32 v95, vcc, 1.0, v56, 1.0
	v_mul_f32_e32 v96, v95, v94
	v_fma_f32 v97, -v57, v96, v95
	v_fmac_f32_e32 v96, v97, v94
	v_fma_f32 v57, -v57, v96, v95
	v_div_fmas_f32 v57, v57, v94, v96
	v_div_fixup_f32 v56, v57, v56, 1.0
	v_pk_mul_f32 v[64:65], v[64:65], v[56:57] op_sel_hi:[1,0]
	v_pk_mul_f32 v[46:47], v[46:47], v[56:57] op_sel_hi:[1,0]
	s_waitcnt vmcnt(0)
	v_pk_mul_f32 v[38:39], v[38:39], v[64:65]
	v_pk_mul_f32 v[40:41], v[40:41], v[46:47]
	v_cvt_pk_bf16_f32 v38, v38, v39
	v_cvt_pk_bf16_f32 v39, v40, v41
	v_pk_mul_f32 v[40:41], v[62:63], v[56:57] op_sel_hi:[1,0]
	v_pk_mul_f32 v[46:47], v[88:89], v[56:57] op_sel_hi:[1,0]
	v_pk_mul_f32 v[34:35], v[34:35], v[40:41]
	s_nop 0
	v_cvt_pk_bf16_f32 v40, v34, v35
	v_pk_mul_f32 v[34:35], v[60:61], v[56:57] op_sel_hi:[1,0]
	s_nop 0
	v_pk_mul_f32 v[34:35], v[36:37], v[34:35]
	s_nop 0
	v_cvt_pk_bf16_f32 v41, v34, v35
	global_store_dwordx4 v[42:43], v[38:41], off
	s_nop 1
	v_pk_mul_f32 v[38:39], v[202:203], v[46:47]
	v_pk_mul_f32 v[46:47], v[50:51], v[56:57] op_sel_hi:[1,0]
	v_cvt_pk_bf16_f32 v38, v38, v39
	v_pk_mul_f32 v[40:41], v[204:205], v[46:47]
	v_pk_mul_f32 v[46:47], v[92:93], v[56:57] op_sel_hi:[1,0]
	v_cvt_pk_bf16_f32 v39, v40, v41
	v_pk_mul_f32 v[40:41], v[86:87], v[56:57] op_sel_hi:[1,0]
	s_nop 0
	v_pk_mul_f32 v[34:35], v[198:199], v[40:41]
	s_nop 0
	v_cvt_pk_bf16_f32 v40, v34, v35
	v_pk_mul_f32 v[34:35], v[84:85], v[56:57] op_sel_hi:[1,0]
	s_nop 0
	v_pk_mul_f32 v[34:35], v[200:201], v[34:35]
	s_nop 0
	v_cvt_pk_bf16_f32 v41, v34, v35
	global_store_dwordx4 v[42:43], v[38:41], off offset:16
	s_nop 1
	v_pk_mul_f32 v[38:39], v[226:227], v[46:47]
	v_pk_mul_f32 v[46:47], v[54:55], v[56:57] op_sel_hi:[1,0]
	v_cvt_pk_bf16_f32 v38, v38, v39
	v_pk_mul_f32 v[40:41], v[228:229], v[46:47]
	v_pk_mul_f32 v[46:47], v[52:53], v[56:57] op_sel_hi:[1,0]
	v_cvt_pk_bf16_f32 v39, v40, v41
	v_pk_mul_f32 v[40:41], v[90:91], v[56:57] op_sel_hi:[1,0]
	s_nop 0
	v_pk_mul_f32 v[34:35], v[206:207], v[40:41]
	s_nop 0
	v_cvt_pk_bf16_f32 v40, v34, v35
	v_pk_mul_f32 v[34:35], v[48:49], v[56:57] op_sel_hi:[1,0]
	s_nop 0
	v_pk_mul_f32 v[34:35], v[208:209], v[34:35]
	s_nop 0
	v_cvt_pk_bf16_f32 v41, v34, v35
	global_store_dwordx4 v[42:43], v[38:41], off offset:32
	s_nop 1
	v_pk_mul_f32 v[38:39], v[234:235], v[46:47]
	v_pk_mul_f32 v[46:47], v[58:59], v[56:57] op_sel_hi:[1,0]
	v_cvt_pk_bf16_f32 v38, v38, v39
	v_pk_mul_f32 v[40:41], v[236:237], v[46:47] op_sel:[0,1] op_sel_hi:[1,0]
	s_nop 0
	v_cvt_pk_bf16_f32 v39, v40, v41
	v_pk_mul_f32 v[40:41], v[82:83], v[56:57] op_sel_hi:[1,0]
	s_nop 0
	v_pk_mul_f32 v[34:35], v[230:231], v[40:41] op_sel:[0,1] op_sel_hi:[1,0]
	s_nop 0
	v_cvt_pk_bf16_f32 v40, v34, v35
	v_pk_mul_f32 v[34:35], v[44:45], v[56:57] op_sel_hi:[1,0]
	s_nop 0
	v_pk_mul_f32 v[34:35], v[232:233], v[34:35] op_sel:[0,1] op_sel_hi:[1,0]
	s_nop 0
	v_cvt_pk_bf16_f32 v41, v34, v35
	global_store_dwordx4 v[42:43], v[38:41], off offset:48
	s_barrier
	s_cbranch_scc1 .LBB0_1388

; DI unsigned cvtpk(float lo, float hi) { f32x2_t v = {lo, hi}; bf16x2_t b = __builtin_convertvector(v, bf16x2_t); return __builtin_bit_cast(unsigned, b); }
; #define MFMA32(a, b, c) __builtin_amdgcn_mfma_f32_32x32x16_bf16((a), (b), (c), 0, 0, 0)
; template <bool GLA, int MODE> ...
;     ...
;             for (int kt = 0; kt < KT; ++kt)
; #pragma unroll
;                 for (int s = 0; s < 2; ++s) {
;                     u32x4 pw; pw.x = cvtpk(S[kt][8 * s + 0], S[kt][8 * s + 1]); pw.y = cvtpk(S[kt][8 * s + 2], S[kt][8 * s + 3]); pw.z = cvtpk(S[kt][8 * s + 4], S[kt][8 * s + 5]); pw.w = cvtpk(S[kt][8 * s + 6], S[kt][8 * s + 7]);
;                     const bf16x8 sb = __builtin_bit_cast(bf16x8, pw);
; #pragma unroll
;                     for (int it = 0; it < 2; ++it) {
;                         const unsigned char* qp = lds + S_QE + (32 * it + r) * S_QES + (hu * DK + 32 * kt + 16 * s + 4 * hh) * 2;
;                         const u32x2 lo = *(const u32x2*)qp, hi = *(const u32x2*)(qp + 16);
;                         u32x4 av; av.x = lo.x; av.y = lo.y; av.z = hi.x; av.w = hi.y;
;                         oa[it] = MFMA32(__builtin_bit_cast(bf16x8, av), sb, oa[it]);
;                     }
;                 }
; #pragma unroll
;         for (int i = 0; i < 4; ++i) *(u32x4*)(lds + S_VT + (tid >> 1) * S_TS + (16 * i + 8 * (tid & 1)) * 2) = vv[i];
;             __syncthreads();
;         }
; #pragma unroll
;         for (int js = 0; js < 4; ++js) {
;             const bf16x8 vb = *(const bf16x8*)(lds + S_VT + (hu * DVH + dv0 + r) * S_TS + (16 * js + 8 * hh) * 2);
;             if (MODE == 0) {
;                 if (js < 2) { const bf16x8 a0 = *(const bf16x8*)(lds + S_ATT + hu * 64 * S_TS + r * S_TS + (16 * js + 8 * hh) * 2); oa[0] = MFMA32(a0, vb, oa[0]); }
;                 { const bf16x8 a1 = *(const bf16x8*)(lds + S_ATT + hu * 64 * S_TS + (32 + r) * S_TS + (16 * js + 8 * hh) * 2); oa[1] = MFMA32(a1, vb, oa[1]); }
;             }
; #pragma unroll
;             for (int kt = 0; kt < KT; ++kt) {
;                 const bf16x8 ka = *(const bf16x8*)(lds + S_KST + (hu * DK + 32 * kt + r) * S_TS + (16 * js + 8 * hh) * 2);
;                 S[kt] = MFMA32(ka, vb, S[kt]);
.LBB0_1681:
	s_or_b64 exec, exec, s[86:87]
	ds_read2_b64 v[70:73], v160 offset1:2
	ds_read2_b64 v[168:171], v160 offset0:4 offset1:6
	v_cvt_pk_bf16_f32 v66, v2, v3
	v_cvt_pk_bf16_f32 v67, v4, v5
	v_cvt_pk_bf16_f32 v68, v6, v7
	v_cvt_pk_bf16_f32 v69, v8, v9
	v_add_u32_e32 v176, 0x2000, v160
	v_cvt_pk_bf16_f32 v172, v10, v11
	s_waitcnt lgkmcnt(1)
	v_mfma_f32_32x32x16_bf16 v[82:97], v[70:73], v[66:69], 0
	ds_read2_b64 v[70:73], v176 offset0:64 offset1:66
	v_cvt_pk_bf16_f32 v173, v12, v13
	v_cvt_pk_bf16_f32 v174, v14, v15
	v_cvt_pk_bf16_f32 v175, v16, v17
	s_add_i32 s85, s85, 64
	s_cmp_eq_u32 s38, s6
	s_waitcnt lgkmcnt(1)
	v_mfma_f32_32x32x16_bf16 v[82:97], v[168:171], v[172:175], v[82:97]
	ds_read2_b64 v[168:171], v176 offset0:68 offset1:70
	s_waitcnt lgkmcnt(1)
	v_mfma_f32_32x32x16_bf16 v[66:81], v[70:73], v[66:69], 0
	s_waitcnt lgkmcnt(0)
	v_mfma_f32_32x32x16_bf16 v[66:81], v[168:171], v[172:175], v[66:81]
	ds_read2_b64 v[172:175], v160 offset0:8 offset1:10
	v_cvt_pk_bf16_f32 v168, v18, v19
	v_cvt_pk_bf16_f32 v169, v20, v21
	v_cvt_pk_bf16_f32 v170, v22, v23
	v_cvt_pk_bf16_f32 v171, v24, v25
	s_waitcnt lgkmcnt(0)
	s_nop 0
	v_mfma_f32_32x32x16_bf16 v[82:97], v[172:175], v[168:171], v[82:97]
	ds_read2_b64 v[172:175], v176 offset0:72 offset1:74
	s_waitcnt lgkmcnt(0)
	v_mfma_f32_32x32x16_bf16 v[66:81], v[172:175], v[168:171], v[66:81]
	ds_read2_b64 v[172:175], v160 offset0:12 offset1:14
	v_cvt_pk_bf16_f32 v168, v26, v27
	v_cvt_pk_bf16_f32 v169, v28, v29
	v_cvt_pk_bf16_f32 v170, v30, v31
	v_cvt_pk_bf16_f32 v171, v32, v33
	s_waitcnt lgkmcnt(0)
	s_nop 0
	v_mfma_f32_32x32x16_bf16 v[82:97], v[172:175], v[168:171], v[82:97]
	ds_read2_b64 v[172:175], v176 offset0:76 offset1:78
	s_waitcnt lgkmcnt(0)
	v_mfma_f32_32x32x16_bf16 v[66:81], v[172:175], v[168:171], v[66:81]
	ds_read2_b64 v[172:175], v160 offset0:16 offset1:18
	v_cvt_pk_bf16_f32 v168, v34, v35
	v_cvt_pk_bf16_f32 v169, v36, v37
	v_cvt_pk_bf16_f32 v170, v38, v39
	v_cvt_pk_bf16_f32 v171, v40, v41
	s_waitcnt lgkmcnt(0)
	s_nop 0
	v_mfma_f32_32x32x16_bf16 v[82:97], v[172:175], v[168:171], v[82:97]
	ds_read2_b64 v[172:175], v176 offset0:80 offset1:82
	s_waitcnt lgkmcnt(0)
	v_mfma_f32_32x32x16_bf16 v[66:81], v[172:175], v[168:171], v[66:81]
	ds_read2_b64 v[172:175], v160 offset0:20 offset1:22
	v_cvt_pk_bf16_f32 v168, v42, v43
	v_cvt_pk_bf16_f32 v169, v44, v45
	v_cvt_pk_bf16_f32 v170, v46, v47
	v_cvt_pk_bf16_f32 v171, v48, v49
	s_waitcnt lgkmcnt(0)
	s_nop 0
	v_mfma_f32_32x32x16_bf16 v[82:97], v[172:175], v[168:171], v[82:97]
	ds_read2_b64 v[172:175], v176 offset0:84 offset1:86
	s_waitcnt lgkmcnt(0)
	v_mfma_f32_32x32x16_bf16 v[66:81], v[172:175], v[168:171], v[66:81]
	ds_read2_b64 v[172:175], v160 offset0:24 offset1:26
	v_cvt_pk_bf16_f32 v168, v50, v51
	v_cvt_pk_bf16_f32 v169, v52, v53
	v_cvt_pk_bf16_f32 v170, v54, v55
	v_cvt_pk_bf16_f32 v171, v56, v57
	s_waitcnt lgkmcnt(0)
	s_nop 0
	v_mfma_f32_32x32x16_bf16 v[82:97], v[172:175], v[168:171], v[82:97]
	ds_read2_b64 v[172:175], v176 offset0:88 offset1:90
	s_waitcnt lgkmcnt(0)
	v_mfma_f32_32x32x16_bf16 v[66:81], v[172:175], v[168:171], v[66:81]
	ds_read2_b64 v[172:175], v160 offset0:28 offset1:30
	v_cvt_pk_bf16_f32 v168, v58, v59
	v_cvt_pk_bf16_f32 v169, v60, v61
	v_cvt_pk_bf16_f32 v170, v62, v63
	v_cvt_pk_bf16_f32 v171, v64, v65
	s_waitcnt lgkmcnt(0)
	s_nop 0
	v_mfma_f32_32x32x16_bf16 v[82:97], v[172:175], v[168:171], v[82:97]
	ds_read2_b64 v[172:175], v176 offset0:92 offset1:94
	ds_write_b128 v161, v[122:125] offset:53248
	ds_write_b128 v161, v[126:129] offset:53280
	s_waitcnt vmcnt(1)
	ds_write_b128 v161, v[130:133] offset:53312
	s_waitcnt vmcnt(0)
	ds_write_b128 v161, v[134:137] offset:53344
	s_waitcnt lgkmcnt(0)
	s_barrier
	ds_read_b128 v[122:125], v162 offset:53248
	ds_read_b128 v[126:129], v162 offset:53280
	ds_read_b128 v[130:133], v163
	ds_read_b128 v[134:137], v163 offset:32
	v_mfma_f32_32x32x16_bf16 v[66:81], v[172:175], v[168:171], v[66:81]
	s_waitcnt lgkmcnt(1)
	v_mfma_f32_32x32x16_bf16 v[82:97], v[130:133], v[122:125], v[82:97]
	ds_read_b128 v[130:133], v163 offset:4608
	ds_read_b128 v[168:171], v164 offset:34816
	ds_read_b128 v[172:175], v164 offset:34848
	s_waitcnt lgkmcnt(1)
	v_mfma_f32_32x32x16_bf16 v[2:17], v[168:171], v[122:125], v[2:17]
	ds_read_b128 v[168:171], v164 offset:39424
	s_waitcnt lgkmcnt(0)
	v_mfma_f32_32x32x16_bf16 v[18:33], v[168:171], v[122:125], v[18:33]
	ds_read_b128 v[168:171], v164 offset:44032
	s_waitcnt lgkmcnt(0)
	v_mfma_f32_32x32x16_bf16 v[34:49], v[168:171], v[122:125], v[34:49]
	ds_read_b128 v[168:171], v164 offset:48640
	s_waitcnt lgkmcnt(0)
	v_mfma_f32_32x32x16_bf16 v[50:65], v[168:171], v[122:125], v[50:65]
	v_mfma_f32_32x32x16_bf16 v[66:81], v[130:133], v[122:125], v[66:81]
	ds_read_b128 v[122:125], v163 offset:4640
	ds_read_b128 v[130:133], v164 offset:39456
	s_waitcnt lgkmcnt(0)
	v_mfma_f32_32x32x16_bf16 v[18:33], v[130:133], v[126:129], v[18:33]
	ds_read_b128 v[130:133], v164 offset:44064
	s_waitcnt lgkmcnt(0)
	v_mfma_f32_32x32x16_bf16 v[34:49], v[130:133], v[126:129], v[34:49]
	ds_read_b128 v[130:133], v164 offset:48672
	v_mfma_f32_32x32x16_bf16 v[2:17], v[172:175], v[126:129], v[2:17]
	v_mfma_f32_32x32x16_bf16 v[82:97], v[134:137], v[126:129], v[82:97]
	s_waitcnt lgkmcnt(0)
	v_mfma_f32_32x32x16_bf16 v[50:65], v[130:133], v[126:129], v[50:65]
	s_nop 9
	v_cvt_pk_bf16_f32 v82, v82, s0
	v_mfma_f32_32x32x16_bf16 v[66:81], v[122:125], v[126:129], v[66:81]
	ds_read_b128 v[122:125], v162 offset:53312
	ds_read_b128 v[126:129], v163 offset:4672
	ds_read_b128 v[130:133], v164 offset:34880
	s_waitcnt lgkmcnt(0)
	v_mfma_f32_32x32x16_bf16 v[2:17], v[130:133], v[122:125], v[2:17]
	ds_read_b128 v[130:133], v164 offset:39488
	s_waitcnt lgkmcnt(0)
; DI unsigned short f2bf(float f) { return (unsigned short)(cvtpk(f, 0.f) & 0xffffu); }
; DI int crow(int g, int h) { return (g & 3) + 8 * (g >> 2) + 4 * h; }
; #define MFMA32(a, b, c) __builtin_amdgcn_mfma_f32_32x32x16_bf16((a), (b), (c), 0, 0, 0)
; template <bool GLA, int MODE> ...
;     ...
; #pragma unroll
;         for (int js = 0; js < 4; ++js) {
;             const bf16x8 vb = *(const bf16x8*)(lds + S_VT + (hu * DVH + dv0 + r) * S_TS + (16 * js + 8 * hh) * 2);
;             if (MODE == 0) {
;                 if (js < 2) { const bf16x8 a0 = *(const bf16x8*)(lds + S_ATT + hu * 64 * S_TS + r * S_TS + (16 * js + 8 * hh) * 2); oa[0] = MFMA32(a0, vb, oa[0]); }
;                 { const bf16x8 a1 = *(const bf16x8*)(lds + S_ATT + hu * 64 * S_TS + (32 + r) * S_TS + (16 * js + 8 * hh) * 2); oa[1] = MFMA32(a1, vb, oa[1]); }
;             }
; #pragma unroll
;             for (int kt = 0; kt < KT; ++kt) {
;                 const bf16x8 ka = *(const bf16x8*)(lds + S_KST + (hu * DK + 32 * kt + r) * S_TS + (16 * js + 8 * hh) * 2);
;                 S[kt] = MFMA32(ka, vb, S[kt]);
;             }
;         }
; #pragma unroll
;         for (int kt = 0; kt < KT; ++kt)
; #pragma unroll
;             for (int g = 0; g < 16; ++g) S[kt][g] *= DEC[hu * DK + 32 * kt + crow(g, hh)];
;         __syncthreads();
;         if (MODE == 0) {
;             {
;                 unsigned short* OB = (unsigned short*)(lds + S_OB);
; #pragma unroll
;                 for (int it = 0; it < 2; ++it)
; #pragma unroll
;                     for (int g = 0; g < 16; ++g) OB[(32 * it + crow(g, hh)) * (S_OBS / 2) + hu * DVH + dv0 + r] = f2bf(oa[it][g]);
	v_mfma_f32_32x32x16_bf16 v[18:33], v[130:133], v[122:125], v[18:33]
	ds_read_b128 v[130:133], v164 offset:44096
	s_waitcnt lgkmcnt(0)
	v_mfma_f32_32x32x16_bf16 v[34:49], v[130:133], v[122:125], v[34:49]
	ds_read_b128 v[130:133], v164 offset:48704
	s_waitcnt lgkmcnt(0)
	v_mfma_f32_32x32x16_bf16 v[50:65], v[130:133], v[122:125], v[50:65]
	v_mfma_f32_32x32x16_bf16 v[66:81], v[126:129], v[122:125], v[66:81]
	ds_read_b128 v[122:125], v162 offset:53344
	ds_read_b128 v[126:129], v163 offset:4704
	ds_read_b128 v[130:133], v164 offset:34912
	s_waitcnt lgkmcnt(0)
	v_mfma_f32_32x32x16_bf16 v[2:17], v[130:133], v[122:125], v[2:17]
	ds_read_b128 v[130:133], v164 offset:39520
	s_waitcnt lgkmcnt(0)
	v_mfma_f32_32x32x16_bf16 v[18:33], v[130:133], v[122:125], v[18:33]
	ds_read_b128 v[130:133], v164 offset:44128
	s_waitcnt lgkmcnt(0)
	v_mfma_f32_32x32x16_bf16 v[34:49], v[130:133], v[122:125], v[34:49]
	ds_read_b128 v[130:133], v164 offset:48736
	s_waitcnt lgkmcnt(0)
	v_mfma_f32_32x32x16_bf16 v[50:65], v[130:133], v[122:125], v[50:65]
	v_mfma_f32_32x32x16_bf16 v[66:81], v[126:129], v[122:125], v[66:81]
	ds_read_b128 v[122:125], v165
	ds_read_b128 v[126:129], v165 offset:32
	s_waitcnt lgkmcnt(1)
	v_mul_f32_e64 v2, v2, v122
	v_mul_f32_e64 v3, v3, v123
	v_pk_mul_f32 v[4:5], v[4:5], v[124:125]
	ds_read_b128 v[122:125], v165 offset:64
	s_nop 4
	v_cvt_pk_bf16_f32 v66, v66, s0
	s_waitcnt lgkmcnt(1)
	v_pk_mul_f32 v[6:7], v[6:7], v[126:127]
	v_pk_mul_f32 v[8:9], v[8:9], v[128:129]
	s_waitcnt lgkmcnt(0)
	v_pk_mul_f32 v[10:11], v[10:11], v[122:123]
	v_pk_mul_f32 v[12:13], v[12:13], v[124:125]
	ds_read_b128 v[122:125], v165 offset:96
	s_waitcnt lgkmcnt(0)
	v_pk_mul_f32 v[14:15], v[14:15], v[122:123]
	v_pk_mul_f32 v[16:17], v[16:17], v[124:125]
	ds_read_b128 v[122:125], v165 offset:128
	s_waitcnt lgkmcnt(0)
	v_pk_mul_f32 v[18:19], v[18:19], v[122:123]
	v_pk_mul_f32 v[20:21], v[20:21], v[124:125]
	ds_read_b128 v[122:125], v165 offset:160
	s_waitcnt lgkmcnt(0)
	v_pk_mul_f32 v[22:23], v[22:23], v[122:123]
	v_pk_mul_f32 v[24:25], v[24:25], v[124:125]
	ds_read_b128 v[122:125], v165 offset:192
	s_waitcnt lgkmcnt(0)
	v_pk_mul_f32 v[26:27], v[26:27], v[122:123]
	v_pk_mul_f32 v[28:29], v[28:29], v[124:125]
	ds_read_b128 v[122:125], v165 offset:224
	s_waitcnt lgkmcnt(0)
	v_pk_mul_f32 v[30:31], v[30:31], v[122:123]
	v_pk_mul_f32 v[32:33], v[32:33], v[124:125]
	ds_read_b128 v[122:125], v165 offset:256
	s_waitcnt lgkmcnt(0)
	v_pk_mul_f32 v[34:35], v[34:35], v[122:123]
	v_pk_mul_f32 v[36:37], v[36:37], v[124:125]
	ds_read_b128 v[122:125], v165 offset:288
	s_waitcnt lgkmcnt(0)
	v_pk_mul_f32 v[38:39], v[38:39], v[122:123]
	v_pk_mul_f32 v[40:41], v[40:41], v[124:125]
	ds_read_b128 v[122:125], v165 offset:320
	s_waitcnt lgkmcnt(0)
	v_pk_mul_f32 v[42:43], v[42:43], v[122:123]
	v_pk_mul_f32 v[44:45], v[44:45], v[124:125]
	ds_read_b128 v[122:125], v165 offset:352
	s_waitcnt lgkmcnt(0)
	v_pk_mul_f32 v[46:47], v[46:47], v[122:123]
	v_pk_mul_f32 v[48:49], v[48:49], v[124:125]
	ds_read_b128 v[122:125], v165 offset:384
	s_waitcnt lgkmcnt(0)
	v_pk_mul_f32 v[50:51], v[50:51], v[122:123]
	v_pk_mul_f32 v[52:53], v[52:53], v[124:125]
	ds_read_b128 v[122:125], v165 offset:416
	s_waitcnt lgkmcnt(0)
	v_pk_mul_f32 v[54:55], v[54:55], v[122:123]
	v_pk_mul_f32 v[56:57], v[56:57], v[124:125]
	ds_read_b128 v[122:125], v165 offset:448
	s_waitcnt lgkmcnt(0)
	v_pk_mul_f32 v[58:59], v[58:59], v[122:123]
	v_pk_mul_f32 v[60:61], v[60:61], v[124:125]
	ds_read_b128 v[122:125], v165 offset:480
	s_waitcnt lgkmcnt(0)
	s_barrier
	ds_write_b16 v166, v66 offset:16896
	v_cvt_pk_bf16_f32 v66, v67, s0
	ds_write_b16 v166, v66 offset:17424
	v_cvt_pk_bf16_f32 v66, v68, s0
	ds_write_b16 v166, v66 offset:17952
	v_cvt_pk_bf16_f32 v66, v69, s0
	ds_write_b16 v166, v66 offset:18480
	v_cvt_pk_bf16_f32 v66, v70, s0
	ds_write_b16 v166, v66 offset:21120
	v_cvt_pk_bf16_f32 v66, v71, s0
	ds_write_b16 v166, v66 offset:21648
	v_cvt_pk_bf16_f32 v66, v72, s0
	ds_write_b16 v166, v66 offset:22176
	v_cvt_pk_bf16_f32 v66, v73, s0
	ds_write_b16 v166, v66 offset:22704
	v_cvt_pk_bf16_f32 v66, v74, s0
	ds_write_b16 v166, v66 offset:25344
	v_cvt_pk_bf16_f32 v66, v75, s0
	ds_write_b16 v166, v82
	v_cvt_pk_bf16_f32 v82, v83, s0
	ds_write_b16 v166, v66 offset:25872
	v_cvt_pk_bf16_f32 v66, v76, s0
	ds_write_b16 v166, v82 offset:528
	v_cvt_pk_bf16_f32 v82, v84, s0
	ds_write_b16 v166, v66 offset:26400
	v_cvt_pk_bf16_f32 v66, v77, s0
	ds_write_b16 v166, v82 offset:1056
	v_cvt_pk_bf16_f32 v82, v85, s0
	ds_write_b16 v166, v66 offset:26928
	v_cvt_pk_bf16_f32 v66, v78, s0
	ds_write_b16 v166, v82 offset:1584
	v_cvt_pk_bf16_f32 v82, v86, s0
	ds_write_b16 v166, v66 offset:29568
	v_cvt_pk_bf16_f32 v66, v79, s0
	ds_write_b16 v166, v82 offset:4224
	v_cvt_pk_bf16_f32 v82, v87, s0
	ds_write_b16 v166, v66 offset:30096
	v_cvt_pk_bf16_f32 v66, v80, s0
	ds_write_b16 v166, v82 offset:4752
	v_cvt_pk_bf16_f32 v82, v88, s0
	ds_write_b16 v166, v66 offset:30624
	v_cvt_pk_bf16_f32 v66, v81, s0
	v_and_b32_e32 v67, 64, v220
	ds_write_b16 v166, v82 offset:5280
	v_cvt_pk_bf16_f32 v82, v89, s0
	ds_write_b16 v166, v66 offset:31152
	v_xor_b32_e32 v66, 1, v220
	v_add_u32_e32 v67, 64, v67
	ds_write_b16 v166, v82 offset:5808
	v_cvt_pk_bf16_f32 v82, v90, s0
	v_cmp_lt_i32_e32 vcc, v66, v67
	ds_write_b16 v166, v82 offset:8448
	v_cvt_pk_bf16_f32 v82, v91, s0
	v_cndmask_b32_e32 v66, v220, v66, vcc
	ds_write_b16 v166, v82 offset:8976
	v_cvt_pk_bf16_f32 v82, v92, s0
	v_lshlrev_b32_e32 v194, 2, v66
	v_xor_b32_e32 v66, 2, v220
	ds_write_b16 v166, v82 offset:9504
	v_cvt_pk_bf16_f32 v82, v93, s0
	v_cmp_lt_i32_e32 vcc, v66, v67
	ds_write_b16 v166, v82 offset:10032
	v_cvt_pk_bf16_f32 v82, v94, s0
	v_cndmask_b32_e32 v66, v220, v66, vcc
	ds_write_b16 v166, v82 offset:12672
	v_cvt_pk_bf16_f32 v82, v95, s0
	v_lshlrev_b32_e32 v195, 2, v66
	v_xor_b32_e32 v66, 4, v220
	ds_write_b16 v166, v82 offset:13200
	v_cvt_pk_bf16_f32 v82, v96, s0
	v_cmp_lt_i32_e32 vcc, v66, v67
	ds_write_b16 v166, v82 offset:13728
	v_cvt_pk_bf16_f32 v82, v97, s0
	v_cndmask_b32_e32 v66, v220, v66, vcc
	ds_write_b16 v166, v82 offset:14256
	s_waitcnt lgkmcnt(0)
	s_barrier
; DI float bflo(unsigned w) { return __uint_as_float(w << 16); }
; DI float bfhi(unsigned w) { return __uint_as_float(w & 0xffff0000u); }
; template <bool GLA, int MODE> ...
;     ...
;             {
;                 const int i = tid >> 3, p = tid & 7;
;                 const u32x4* src = (const u32x4*)(lds + S_OB + i * S_OBS + p * 64);
;                 float x[32];
; #pragma unroll
;                 for (int q = 0; q < 4; ++q) { const u32x4 w = src[q];
;                     x[8 * q + 0] = bflo(w.x); x[8 * q + 1] = bfhi(w.x); x[8 * q + 2] = bflo(w.y); x[8 * q + 3] = bfhi(w.y);
;                     x[8 * q + 4] = bflo(w.z); x[8 * q + 5] = bfhi(w.z); x[8 * q + 6] = bflo(w.w); x[8 * q + 7] = bfhi(w.w); }
;                 float s = 0.f;
;                 if (!GLA) {
; #pragma unroll
;                     for (int q = 0; q < 32; ++q) s += x[q];
;                     s += __shfl_xor(s, 1); s += __shfl_xor(s, 2);
;                     const float mean = s * (1.f / 128.f);
; #pragma unroll
;                     for (int q = 0; q < 32; ++q) x[q] -= mean;
;                 }
;                 float s2 = 0.f;
; #pragma unroll
;                 for (int q = 0; q < 32; ++q) s2 += x[q] * x[q];
;                 s2 += __shfl_xor(s2, 1); s2 += __shfl_xor(s2, 2); if (GLA) s2 += __shfl_xor(s2, 4);
	ds_read_b128 v[80:83], v167
	ds_read_b128 v[126:129], v167 offset:16
	ds_read_b128 v[130:133], v167 offset:32
	ds_read_b128 v[134:137], v167 offset:48
	v_lshlrev_b32_e32 v196, 2, v66
	v_add_u32_e32 v66, s8, v154
	v_ashrrev_i32_e32 v67, 31, v66
	v_lshlrev_b64 v[66:67], 11, v[66:67]
	s_waitcnt lgkmcnt(3)
	v_lshlrev_b32_e32 v176, 16, v80
	v_and_b32_e32 v177, 0xffff0000, v80
	v_pk_mul_f32 v[64:65], v[64:65], v[124:125]
	v_lshl_add_u64 v[78:79], v[146:147], 0, v[66:67]
	global_load_dwordx4 v[66:69], v[144:145], off offset:16
	global_load_dwordx4 v[70:73], v[144:145], off
	global_load_dwordx4 v[198:201], v[144:145], off offset:48
	global_load_dwordx4 v[202:205], v[144:145], off offset:32
	global_load_dwordx4 v[206:209], v[144:145], off offset:80
	global_load_dwordx4 v[226:229], v[144:145], off offset:64
	global_load_dwordx4 v[230:233], v[144:145], off offset:112
	global_load_dwordx4 v[234:237], v[144:145], off offset:96
	v_lshlrev_b32_e32 v124, 16, v81
	v_and_b32_e32 v125, 0xffff0000, v81
	v_pk_mul_f32 v[178:179], v[176:177], v[176:177]
	v_pk_mul_f32 v[174:175], v[124:125], v[124:125]
	v_add_f32_e32 v178, v178, v179
	v_lshlrev_b32_e32 v96, 16, v82
	v_and_b32_e32 v97, 0xffff0000, v82
	v_add_f32_e32 v174, v174, v178
	v_pk_mul_f32 v[172:173], v[96:97], v[96:97]
	v_add_f32_e32 v174, v175, v174
	v_lshlrev_b32_e32 v92, 16, v83
	v_and_b32_e32 v93, 0xffff0000, v83
	v_add_f32_e32 v172, v172, v174
	v_pk_mul_f32 v[170:171], v[92:93], v[92:93]
	v_add_f32_e32 v172, v173, v172
	s_waitcnt lgkmcnt(2)
	v_lshlrev_b32_e32 v184, 16, v126
	v_and_b32_e32 v185, 0xffff0000, v126
	v_add_f32_e32 v170, v170, v172
	v_pk_mul_f32 v[62:63], v[62:63], v[122:123]
	v_lshlrev_b32_e32 v122, 16, v127
	v_and_b32_e32 v123, 0xffff0000, v127
	v_pk_mul_f32 v[126:127], v[184:185], v[184:185]
	v_add_f32_e32 v170, v171, v170
	v_add_f32_e32 v126, v126, v170
	v_pk_mul_f32 v[182:183], v[122:123], v[122:123]
	v_add_f32_e32 v126, v127, v126
	v_lshlrev_b32_e32 v90, 16, v128
	v_and_b32_e32 v91, 0xffff0000, v128
	v_add_f32_e32 v126, v182, v126
	v_lshlrev_b32_e32 v86, 16, v129
	v_and_b32_e32 v87, 0xffff0000, v129
	v_pk_mul_f32 v[128:129], v[90:91], v[90:91]
	v_add_f32_e32 v126, v183, v126
	v_add_f32_e32 v126, v128, v126
	v_pk_mul_f32 v[180:181], v[86:87], v[86:87]
	v_add_f32_e32 v126, v129, v126
	s_waitcnt lgkmcnt(1)
	v_lshlrev_b32_e32 v190, 16, v130
	v_and_b32_e32 v191, 0xffff0000, v130
	v_add_f32_e32 v126, v180, v126
	v_lshlrev_b32_e32 v88, 16, v131
	v_and_b32_e32 v89, 0xffff0000, v131
	v_pk_mul_f32 v[130:131], v[190:191], v[190:191]
	v_add_f32_e32 v126, v181, v126
	v_add_f32_e32 v126, v130, v126
	v_pk_mul_f32 v[188:189], v[88:89], v[88:89]
	v_add_f32_e32 v126, v131, v126
	v_lshlrev_b32_e32 v82, 16, v132
	v_and_b32_e32 v83, 0xffff0000, v132
	v_add_f32_e32 v126, v188, v126
	v_lshlrev_b32_e32 v80, 16, v133
	v_and_b32_e32 v81, 0xffff0000, v133
	v_pk_mul_f32 v[132:133], v[82:83], v[82:83]
	v_add_f32_e32 v126, v189, v126
	v_add_f32_e32 v126, v132, v126
	v_pk_mul_f32 v[186:187], v[80:81], v[80:81]
	v_add_f32_e32 v126, v133, v126
	s_waitcnt lgkmcnt(0)
	v_lshlrev_b32_e32 v94, 16, v134
	v_and_b32_e32 v95, 0xffff0000, v134
	v_add_f32_e32 v126, v186, v126
	v_lshlrev_b32_e32 v84, 16, v135
	v_and_b32_e32 v85, 0xffff0000, v135
	v_pk_mul_f32 v[134:135], v[94:95], v[94:95]
	v_add_f32_e32 v126, v187, v126
	v_add_f32_e32 v126, v134, v126
	v_pk_mul_f32 v[192:193], v[84:85], v[84:85]
	v_add_f32_e32 v126, v135, v126
	v_and_b32_e32 v74, 0xffff0000, v136
	v_lshlrev_b32_e32 v75, 16, v136
	v_add_f32_e32 v126, v192, v126
	v_pk_mul_f32 v[168:169], v[74:75], v[74:75]
	v_add_f32_e32 v126, v193, v126
	v_and_b32_e32 v76, 0xffff0000, v137
	v_lshlrev_b32_e32 v77, 16, v137
	v_add_f32_e32 v126, v169, v126
	v_pk_mul_f32 v[136:137], v[76:77], v[76:77]
	v_add_f32_e32 v126, v168, v126
	v_add_f32_e32 v126, v137, v126
	v_add_f32_e32 v126, v136, v126
	ds_bpermute_b32 v127, v194, v126
	s_mov_b32 s8, 0xf800000
	s_waitcnt lgkmcnt(0)
; DI unsigned cvtpk(float lo, float hi) { f32x2_t v = {lo, hi}; bf16x2_t b = __builtin_convertvector(v, bf16x2_t); return __builtin_bit_cast(unsigned, b); }
; template <bool GLA, int MODE> ...
;     ...
;                 s2 += __shfl_xor(s2, 1); s2 += __shfl_xor(s2, 2); if (GLA) s2 += __shfl_xor(s2, 4);
;                 const float rstd = 1.f / sqrtf(s2 * (1.f / DVH) + EPS);
;                 const float* gp = gain + 32 * p;
;                 u32x4* dst = (u32x4*)(OUT + (size_t)(row0 + i) * out_ld + ocol0 + 32 * p);
; #pragma unroll
;                 for (int q = 0; q < 4; ++q) {
;                     u32x4 w;
;                     w.x = cvtpk(x[8 * q + 0] * rstd * gp[8 * q + 0], x[8 * q + 1] * rstd * gp[8 * q + 1]);
;                     w.y = cvtpk(x[8 * q + 2] * rstd * gp[8 * q + 2], x[8 * q + 3] * rstd * gp[8 * q + 3]);
;                     w.z = cvtpk(x[8 * q + 4] * rstd * gp[8 * q + 4], x[8 * q + 5] * rstd * gp[8 * q + 5]);
;                     w.w = cvtpk(x[8 * q + 6] * rstd * gp[8 * q + 6], x[8 * q + 7] * rstd * gp[8 * q + 7]);
;                     dst[q] = w;
;                 }
	v_add_f32_e32 v126, v126, v127
	ds_bpermute_b32 v127, v195, v126
	s_waitcnt lgkmcnt(0)
	v_add_f32_e32 v126, v126, v127
	ds_bpermute_b32 v127, v196, v126
	s_waitcnt lgkmcnt(0)
	v_add_f32_e32 v126, v126, v127
	v_fmamk_f32 v126, v126, 0x3b800000, v214
	v_cmp_gt_f32_e32 vcc, s8, v126
	v_mul_f32_e32 v127, 0x4f800000, v126
	s_nop 0
	v_cndmask_b32_e32 v126, v126, v127, vcc
	v_sqrt_f32_e32 v127, v126
	s_nop 0
	v_add_u32_e32 v128, -1, v127
	v_fma_f32 v129, -v128, v127, v126
	v_cmp_ge_f32_e64 s[86:87], 0, v129
	v_add_u32_e32 v129, 1, v127
	s_nop 0
	v_cndmask_b32_e64 v128, v127, v128, s[86:87]
	v_fma_f32 v127, -v129, v127, v126
	v_cmp_lt_f32_e64 s[86:87], 0, v127
	s_nop 1
	v_cndmask_b32_e64 v127, v128, v129, s[86:87]
	v_mul_f32_e32 v128, 0x37800000, v127
	v_cndmask_b32_e32 v127, v127, v128, vcc
	v_cmp_class_f32_e32 vcc, v126, v215
	s_nop 1
	v_cndmask_b32_e32 v126, v127, v126, vcc
	v_div_scale_f32 v127, s[8:9], v126, v126, 1.0
	v_rcp_f32_e32 v128, v127
	s_nop 0
	v_fma_f32 v129, -v127, v128, 1.0
	v_fmac_f32_e32 v128, v129, v128
	v_div_scale_f32 v129, vcc, 1.0, v126, 1.0
	v_mul_f32_e32 v130, v129, v128
	v_fma_f32 v131, -v127, v130, v129
	v_fmac_f32_e32 v130, v131, v128
	v_fma_f32 v127, -v127, v130, v129
	v_div_fmas_f32 v127, v127, v128, v130
	v_div_fixup_f32 v126, v127, v126, 1.0
	v_pk_mul_f32 v[128:129], v[126:127], v[176:177] op_sel_hi:[0,1]
	v_pk_mul_f32 v[124:125], v[126:127], v[124:125] op_sel_hi:[0,1]
	s_waitcnt vmcnt(0)
	v_pk_mul_f32 v[70:71], v[70:71], v[128:129]
	v_pk_mul_f32 v[72:73], v[72:73], v[124:125]
	v_cvt_pk_bf16_f32 v70, v70, v71
	v_cvt_pk_bf16_f32 v71, v72, v73
	v_pk_mul_f32 v[72:73], v[126:127], v[96:97] op_sel_hi:[0,1]
	v_pk_mul_f32 v[66:67], v[66:67], v[72:73]
	s_nop 0
	v_cvt_pk_bf16_f32 v72, v66, v67
	v_pk_mul_f32 v[66:67], v[126:127], v[92:93] op_sel_hi:[0,1]
	v_pk_mul_f32 v[66:67], v[68:69], v[66:67]
	v_pk_mul_f32 v[92:93], v[126:127], v[184:185] op_sel_hi:[0,1]
	v_cvt_pk_bf16_f32 v73, v66, v67
	global_store_dwordx4 v[78:79], v[70:73], off
	s_nop 1
	v_pk_mul_f32 v[70:71], v[202:203], v[92:93]
	v_pk_mul_f32 v[92:93], v[126:127], v[122:123] op_sel_hi:[0,1]
	v_pk_mul_f32 v[72:73], v[204:205], v[92:93]
	v_cvt_pk_bf16_f32 v70, v70, v71
	v_cvt_pk_bf16_f32 v71, v72, v73
	v_pk_mul_f32 v[72:73], v[126:127], v[90:91] op_sel_hi:[0,1]
	v_pk_mul_f32 v[66:67], v[198:199], v[72:73]
	s_nop 0
	v_cvt_pk_bf16_f32 v72, v66, v67
	v_pk_mul_f32 v[66:67], v[126:127], v[86:87] op_sel_hi:[0,1]
	v_pk_mul_f32 v[66:67], v[200:201], v[66:67]
	v_pk_mul_f32 v[86:87], v[126:127], v[190:191] op_sel_hi:[0,1]
	v_cvt_pk_bf16_f32 v73, v66, v67
	global_store_dwordx4 v[78:79], v[70:73], off offset:16
	s_nop 1
	v_pk_mul_f32 v[70:71], v[226:227], v[86:87]
	v_pk_mul_f32 v[86:87], v[126:127], v[88:89] op_sel_hi:[0,1]
	v_pk_mul_f32 v[72:73], v[228:229], v[86:87]
	v_cvt_pk_bf16_f32 v70, v70, v71
	v_cvt_pk_bf16_f32 v71, v72, v73
	v_pk_mul_f32 v[72:73], v[126:127], v[82:83] op_sel_hi:[0,1]
	v_pk_mul_f32 v[66:67], v[206:207], v[72:73]
	s_nop 0
	v_cvt_pk_bf16_f32 v72, v66, v67
	v_pk_mul_f32 v[66:67], v[126:127], v[80:81] op_sel_hi:[0,1]
	v_pk_mul_f32 v[66:67], v[208:209], v[66:67]
	v_pk_mul_f32 v[80:81], v[126:127], v[94:95] op_sel_hi:[0,1]
	v_cvt_pk_bf16_f32 v73, v66, v67
	global_store_dwordx4 v[78:79], v[70:73], off offset:32
	s_nop 1
	v_pk_mul_f32 v[70:71], v[234:235], v[80:81]
	v_pk_mul_f32 v[80:81], v[126:127], v[84:85] op_sel_hi:[0,1]
	v_pk_mul_f32 v[72:73], v[236:237], v[80:81]
	v_cvt_pk_bf16_f32 v70, v70, v71
	v_cvt_pk_bf16_f32 v71, v72, v73
	v_pk_mul_f32 v[72:73], v[126:127], v[74:75] op_sel_hi:[0,1]
	v_pk_mul_f32 v[66:67], v[230:231], v[72:73] op_sel:[0,1] op_sel_hi:[1,0]
	s_nop 0
	v_cvt_pk_bf16_f32 v72, v66, v67
	v_pk_mul_f32 v[66:67], v[126:127], v[76:77] op_sel_hi:[0,1]
	v_pk_mul_f32 v[66:67], v[232:233], v[66:67] op_sel:[0,1] op_sel_hi:[1,0]
	s_nop 0
	v_cvt_pk_bf16_f32 v73, v66, v67
	global_store_dwordx4 v[78:79], v[70:73], off offset:48
	s_barrier
	s_cbranch_scc1 .LBB0_1690
